# prologue load balance: rotary-table items moved from workgroups 0-31 (which also carry one extra transpose round) to workgroups 224-255
# speedup vs baseline: 1.0220x; 1.0220x over previous
.LBB0_12:
	v_mov_b32_e32 v1, v200
	v_writelane_b32 v251, s2, 0
	s_cmp_lt_u32 s2, 224
	v_readfirstlane_b32 s33, v1
	s_cbranch_scc1 .LBB0_15
	v_and_b32_e32 v2, 7, v200
	v_cvt_f64_u32_e32 v[2:3], v2
	s_mov_b32 s4, 0x69a05c01
	v_ldexp_f64 v[2:3], -v[2:3], -3
	s_mov_b32 s5, 0x402a3ea6
	v_mul_f64 v[2:3], v[2:3], s[4:5]
	s_mov_b32 s5, 0x3fe62e42
	s_mov_b32 s4, 0xfefa39ef
	v_div_scale_f64 v[4:5], s[6:7], s[4:5], s[4:5], v[2:3]
	v_rcp_f64_e32 v[6:7], v[4:5]
	s_mov_b32 s7, 0x3fc99999
	s_mov_b32 s6, 0x9999999a
	s_mov_b32 s9, 0x3fc24924
	v_fma_f64 v[8:9], -v[4:5], v[6:7], 1.0
	v_fmac_f64_e32 v[6:7], v[6:7], v[8:9]
	v_fma_f64 v[8:9], -v[4:5], v[6:7], 1.0
	v_fmac_f64_e32 v[6:7], v[6:7], v[8:9]
	v_div_scale_f64 v[8:9], vcc, v[2:3], s[4:5], v[2:3]
	v_mul_f64 v[10:11], v[8:9], v[6:7]
	v_fma_f64 v[4:5], -v[4:5], v[10:11], v[8:9]
	s_mov_b32 s8, 0x92492492
	s_nop 0
	v_div_fmas_f64 v[4:5], v[4:5], v[6:7], v[10:11]
	v_div_fixup_f64 v[4:5], v[4:5], s[4:5], v[2:3]
	v_rndne_f64_e32 v[4:5], v[4:5]
	s_mov_b32 s5, 0xbfe62e42
	v_fmac_f64_e32 v[2:3], s[4:5], v[4:5]
	v_add_f64 v[6:7], v[2:3], 1.0
	v_mul_f64 v[8:9], v[2:3], 0.5
	s_mov_b32 s5, 0x3fd55555
	s_mov_b32 s4, 0x55555555
	v_mul_f64 v[10:11], v[2:3], v[8:9]
	v_fmac_f64_e32 v[6:7], v[2:3], v[8:9]
	v_mul_f64 v[8:9], v[2:3], s[4:5]
	v_mul_f64 v[12:13], v[8:9], v[10:11]
	v_fmac_f64_e32 v[6:7], v[8:9], v[10:11]
	v_ldexp_f64 v[8:9], v[2:3], -2
	v_mul_f64 v[10:11], v[8:9], v[12:13]
	v_fmac_f64_e32 v[6:7], v[8:9], v[12:13]
	v_mul_f64 v[8:9], v[2:3], s[6:7]
	s_mov_b32 s5, 0x3fc55555
	v_mul_f64 v[12:13], v[8:9], v[10:11]
	v_fmac_f64_e32 v[6:7], v[8:9], v[10:11]
	v_mul_f64 v[8:9], v[2:3], s[4:5]
	v_mul_f64 v[10:11], v[8:9], v[12:13]
	v_fmac_f64_e32 v[6:7], v[8:9], v[12:13]
	v_mul_f64 v[8:9], v[2:3], s[8:9]
	v_mul_f64 v[12:13], v[8:9], v[10:11]
	v_fmac_f64_e32 v[6:7], v[8:9], v[10:11]
	v_ldexp_f64 v[8:9], v[2:3], -3
	s_mov_b32 s11, 0x3fbc71c7
	s_mov_b32 s10, 0x1c71c71c
	v_mul_f64 v[10:11], v[8:9], v[12:13]
	v_fmac_f64_e32 v[6:7], v[8:9], v[12:13]
	v_mul_f64 v[8:9], v[2:3], s[10:11]
	s_mov_b32 s7, 0x3fb99999
	s_mov_b32 s12, 0x745d1746
	v_mul_f64 v[12:13], v[8:9], v[10:11]
	v_fmac_f64_e32 v[6:7], v[8:9], v[10:11]
	v_mul_f64 v[8:9], v[2:3], s[6:7]
	s_mov_b32 s13, 0x3fb745d1
	v_mul_f64 v[10:11], v[8:9], v[12:13]
	v_fmac_f64_e32 v[6:7], v[8:9], v[12:13]
	v_mul_f64 v[8:9], v[2:3], s[12:13]
	s_mov_b32 s13, 0x3fb55555
	s_mov_b32 s12, s4
	s_mov_b32 s14, 0x13b13b14
	v_mul_f64 v[12:13], v[8:9], v[10:11]
	v_fmac_f64_e32 v[6:7], v[8:9], v[10:11]
	v_mul_f64 v[8:9], v[2:3], s[12:13]
	s_mov_b32 s15, 0x3fb3b13b
	v_mul_f64 v[10:11], v[8:9], v[12:13]
	v_fmac_f64_e32 v[6:7], v[8:9], v[12:13]
	v_mul_f64 v[8:9], v[2:3], s[14:15]
	s_mov_b32 s9, 0x3fb24924
	v_mul_f64 v[12:13], v[8:9], v[10:11]
	v_fmac_f64_e32 v[6:7], v[8:9], v[10:11]
	v_mul_f64 v[8:9], v[2:3], s[8:9]
	s_mov_b32 s15, 0x3fb11111
	s_mov_b32 s14, 0x11111111
	v_mul_f64 v[10:11], v[8:9], v[12:13]
	v_fmac_f64_e32 v[6:7], v[8:9], v[12:13]
	v_mul_f64 v[8:9], v[2:3], s[14:15]
	v_mul_f64 v[12:13], v[8:9], v[10:11]
	v_fmac_f64_e32 v[6:7], v[8:9], v[10:11]
	v_ldexp_f64 v[2:3], v[2:3], -4
	v_fmac_f64_e32 v[6:7], v[2:3], v[12:13]
	v_cvt_i32_f64_e32 v2, v[4:5]
	v_ldexp_f64 v[2:3], v[6:7], v2
	v_cvt_f32_f64_e32 v4, v[2:3]
	s_add_u32 s16, s24, 0xda20000
	v_lshlrev_b32_e32 v2, 1, v200
	v_readlane_b32 s88, v251, 0
	s_mov_b32 s18, 0x54442d18
	s_mov_b32 s22, 0x11111111
	s_mov_b32 s28, 0x18618618
	s_mov_b32 s30, 0x16c16c17
	s_mov_b32 s34, 0x29e4129e
	s_mov_b32 s36, 0xf07c1f08
	s_mov_b32 s38, 0xf07c1f08
	s_mov_b32 s40, 0x1a41a41a
	s_mov_b32 s42, 0x16816817
	s_mov_b32 s44, 0x13813814
	s_mov_b32 s46, 0x1e1e1e1e
	s_mov_b32 s48, 0x1ac5701b
	s_mov_b32 s50, 0xfd017f40
	s_mov_b32 s52, 0x308158ed
	s_mov_b32 s54, 0xb51f5e1a
	s_mov_b32 s56, 0x4046ed29
	s_mov_b32 s58, 0x76b981db
	s_mov_b32 s60, 0xb4e81b4f
	s_mov_b32 s62, 0xc201756d
	s_mov_b32 s64, 0x7f9b2ce6
	s_mov_b32 s66, 0x6b015ac0
	s_mov_b32 s68, 0x25d51f87
	s_mov_b32 s70, 0x19e0119e
	s_mov_b32 s72, 0x12d50a0
	s_mov_b32 s74, 0x8421084
	s_mov_b32 s76, 0x1b89401c
	s_mov_b32 s78, 0x4bc01d34
	s_mov_b32 s80, 0x1a01a01a
	s_mov_b32 s82, 0xf601899c
	s_addc_u32 s17, s25, 0
	s_sub_i32 s88, s88, 224
	v_lshl_add_u32 v2, s88, 10, v2
	v_lshl_add_u32 v5, s88, 9, v200
	s_mov_b32 s19, 0x401921fb
	s_mov_b32 s21, 0xc01921fb
	s_mov_b32 s20, s18
	s_mov_b32 s7, 0x3fa99999
	s_mov_b32 s23, 0x3fa11111
	s_mov_b32 s29, 0x3f986186
	s_mov_b32 s9, 0x3f924924
	s_mov_b32 s11, 0x3f8c71c7
	s_mov_b32 s31, 0x3f86c16c
	s_mov_b32 s35, 0x3f829e41
	s_mov_b32 s37, 0x3f7f07c1
	s_mov_b32 s39, 0x3f4f07c1
	s_mov_b32 s41, 0x3f7a41a4
	s_mov_b32 s43, 0x3f768168
	s_mov_b32 s45, 0x3f738138
	s_mov_b32 s15, 0x3f711111
	s_mov_b32 s47, 0x3f6e1e1e
	s_mov_b32 s49, 0x3f6ac570
	s_mov_b32 s51, 0x3f67f405
	s_mov_b32 s53, 0x3f658ed2
	s_mov_b32 s55, 0x3f603091
	s_mov_b32 s57, 0x3f61bb4a
	s_mov_b32 s59, 0x3f5dae60
	s_mov_b32 s61, 0x3f5b4e81
	s_mov_b32 s63, 0x3f5756ca
	s_mov_b32 s65, 0x3f5934c6
	s_mov_b32 s67, 0x3f55ac05
	s_mov_b32 s69, 0x3f542d66
	s_mov_b32 s71, 0x3f519e01
	s_mov_b32 s73, 0x3f52d50a
	s_mov_b32 s75, 0x3f508421
	s_mov_b32 s77, 0x3f4b8940
	s_mov_b32 s79, 0x3f4d347a
	s_mov_b32 s81, 0x3f4a01a0
	s_mov_b32 s83, 0x3f4899c0
	s_lshl_b32 s86, s26, 10
	s_lshl_b32 s87, s26, 9
	s_mov_b32 s85, 0x3f638138
